# skinny_glu K loop: all 16 weight fragment loads of an iteration issued up front, LDS operands double-buffered
# baseline (speedup 1.0000x reference)
; #define LAS __attribute__((address_space(3)))
; template <int KP>
; __device__ __forceinline__ void skinny_tile(const LAS unsigned char* lds, const bf16_t* Bt, int ldb, int n0, int kbeg, int klen, int lane, f32x4& d0, f32x4& d1) {
;     const int rw = lane & 15, q = lane >> 4;
;     const bf16_t* wrow = Bt + (size_t)(n0 + rw) * ldb + 32 * q;
;     const LAS unsigned char* a0 = lds + rw * (KP * 2 + 16) + (kbeg + 32 * q) * 2;
;     const LAS unsigned char* a1 = a0 + 16 * (KP * 2 + 16);
;     d0 = (f32x4){0.f, 0.f, 0.f, 0.f}; d1 = d0;
; #pragma unroll 4
;     for (int k0 = 0; k0 < klen; k0 += 128) {
;         bf16x8 w[4];
; #pragma unroll
;         for (int s = 0; s < 4; ++s) w[s] = *(const bf16x8*)(wrow + k0 + 8 * s);
; #pragma unroll
;         for (int s = 0; s < 4; ++s) { const bf16x8 b0 = *(const LAS bf16x8*)(a0 + k0 * 2 + 16 * s), b1 = *(const LAS bf16x8*)(a1 + k0 * 2 + 16 * s);
;             d0 = __builtin_amdgcn_mfma_f32_16x16x32_bf16(w[s], b0, d0, 0, 0, 0); d1 = __builtin_amdgcn_mfma_f32_16x16x32_bf16(w[s], b1, d1, 0, 0, 0); }
;     }
; }
.LBB0_1150:
	global_load_dwordx4 v[100:103], v[26:27], off offset:-512
	global_load_dwordx4 v[104:107], v[26:27], off offset:-496
	global_load_dwordx4 v[108:111], v[26:27], off offset:-480
	global_load_dwordx4 v[112:115], v[26:27], off offset:-464
	global_load_dwordx4 v[116:119], v[26:27], off offset:-256
	global_load_dwordx4 v[120:123], v[26:27], off offset:-240
	global_load_dwordx4 v[124:127], v[26:27], off offset:-224
	global_load_dwordx4 v[128:131], v[26:27], off offset:-208
	global_load_dwordx4 v[132:135], v[26:27], off
	global_load_dwordx4 v[136:139], v[26:27], off offset:16
	global_load_dwordx4 v[140:143], v[26:27], off offset:32
	global_load_dwordx4 v[144:147], v[26:27], off offset:48
	global_load_dwordx4 v[148:151], v[26:27], off offset:256
	global_load_dwordx4 v[152:155], v[26:27], off offset:272
	global_load_dwordx4 v[156:159], v[26:27], off offset:288
	global_load_dwordx4 v[160:163], v[26:27], off offset:304
	v_lshl_add_u64 v[26:27], v[26:27], 0, s[18:19]
	ds_read_b128 v[36:39], v23
	ds_read_b128 v[40:43], v23 offset:33024
	ds_read_b128 v[44:47], v23 offset:16
	ds_read_b128 v[48:51], v23 offset:33040
	s_waitcnt vmcnt(15) lgkmcnt(2)
	v_mfma_f32_16x16x32_bf16 v[6:9], v[100:103], v[36:39], v[6:9]
	v_mfma_f32_16x16x32_bf16 v[2:5], v[100:103], v[40:43], v[2:5]
	ds_read_b128 v[36:39], v23 offset:32
	ds_read_b128 v[40:43], v23 offset:33056
	s_waitcnt vmcnt(14) lgkmcnt(2)
	v_mfma_f32_16x16x32_bf16 v[6:9], v[104:107], v[44:47], v[6:9]
	v_mfma_f32_16x16x32_bf16 v[2:5], v[104:107], v[48:51], v[2:5]
	ds_read_b128 v[44:47], v23 offset:48
	ds_read_b128 v[48:51], v23 offset:33072
	s_waitcnt vmcnt(13) lgkmcnt(2)
	v_mfma_f32_16x16x32_bf16 v[6:9], v[108:111], v[36:39], v[6:9]
	v_mfma_f32_16x16x32_bf16 v[2:5], v[108:111], v[40:43], v[2:5]
	ds_read_b128 v[36:39], v23 offset:256
	ds_read_b128 v[40:43], v23 offset:33280
	s_waitcnt vmcnt(12) lgkmcnt(2)
	v_mfma_f32_16x16x32_bf16 v[6:9], v[112:115], v[44:47], v[6:9]
	v_mfma_f32_16x16x32_bf16 v[2:5], v[112:115], v[48:51], v[2:5]
	ds_read_b128 v[44:47], v23 offset:272
	ds_read_b128 v[48:51], v23 offset:33296
	s_waitcnt vmcnt(11) lgkmcnt(2)
	v_mfma_f32_16x16x32_bf16 v[6:9], v[116:119], v[36:39], v[6:9]
	v_mfma_f32_16x16x32_bf16 v[2:5], v[116:119], v[40:43], v[2:5]
	ds_read_b128 v[36:39], v23 offset:288
	ds_read_b128 v[40:43], v23 offset:33312
	s_waitcnt vmcnt(10) lgkmcnt(2)
	v_mfma_f32_16x16x32_bf16 v[6:9], v[120:123], v[44:47], v[6:9]
	v_mfma_f32_16x16x32_bf16 v[2:5], v[120:123], v[48:51], v[2:5]
	ds_read_b128 v[44:47], v23 offset:304
	ds_read_b128 v[48:51], v23 offset:33328
	s_waitcnt vmcnt(9) lgkmcnt(2)
	v_mfma_f32_16x16x32_bf16 v[6:9], v[124:127], v[36:39], v[6:9]
	v_mfma_f32_16x16x32_bf16 v[2:5], v[124:127], v[40:43], v[2:5]
	ds_read_b128 v[36:39], v23 offset:512
	ds_read_b128 v[40:43], v23 offset:33536
	s_waitcnt vmcnt(8) lgkmcnt(2)
	v_mfma_f32_16x16x32_bf16 v[6:9], v[128:131], v[44:47], v[6:9]
	v_mfma_f32_16x16x32_bf16 v[2:5], v[128:131], v[48:51], v[2:5]
	ds_read_b128 v[44:47], v23 offset:528
	ds_read_b128 v[48:51], v23 offset:33552
	s_waitcnt vmcnt(7) lgkmcnt(2)
	v_mfma_f32_16x16x32_bf16 v[6:9], v[132:135], v[36:39], v[6:9]
	v_mfma_f32_16x16x32_bf16 v[2:5], v[132:135], v[40:43], v[2:5]
	ds_read_b128 v[36:39], v23 offset:544
	ds_read_b128 v[40:43], v23 offset:33568
	s_waitcnt vmcnt(6) lgkmcnt(2)
	v_mfma_f32_16x16x32_bf16 v[6:9], v[136:139], v[44:47], v[6:9]
	v_mfma_f32_16x16x32_bf16 v[2:5], v[136:139], v[48:51], v[2:5]
	ds_read_b128 v[44:47], v23 offset:560
	ds_read_b128 v[48:51], v23 offset:33584
	s_waitcnt vmcnt(5) lgkmcnt(2)
	v_mfma_f32_16x16x32_bf16 v[6:9], v[140:143], v[36:39], v[6:9]
	v_mfma_f32_16x16x32_bf16 v[2:5], v[140:143], v[40:43], v[2:5]
	ds_read_b128 v[36:39], v23 offset:768
	ds_read_b128 v[40:43], v23 offset:33792
	s_waitcnt vmcnt(4) lgkmcnt(2)
	v_mfma_f32_16x16x32_bf16 v[6:9], v[144:147], v[44:47], v[6:9]
	v_mfma_f32_16x16x32_bf16 v[2:5], v[144:147], v[48:51], v[2:5]
	ds_read_b128 v[44:47], v23 offset:784
	ds_read_b128 v[48:51], v23 offset:33808
	s_waitcnt vmcnt(3) lgkmcnt(2)
	v_mfma_f32_16x16x32_bf16 v[6:9], v[148:151], v[36:39], v[6:9]
	v_mfma_f32_16x16x32_bf16 v[2:5], v[148:151], v[40:43], v[2:5]
	ds_read_b128 v[36:39], v23 offset:800
	ds_read_b128 v[40:43], v23 offset:33824
	s_waitcnt vmcnt(2) lgkmcnt(2)
	v_mfma_f32_16x16x32_bf16 v[6:9], v[152:155], v[44:47], v[6:9]
	v_mfma_f32_16x16x32_bf16 v[2:5], v[152:155], v[48:51], v[2:5]
	ds_read_b128 v[44:47], v23 offset:816
	ds_read_b128 v[48:51], v23 offset:33840
	s_waitcnt vmcnt(1) lgkmcnt(2)
	v_mfma_f32_16x16x32_bf16 v[6:9], v[156:159], v[36:39], v[6:9]
	v_mfma_f32_16x16x32_bf16 v[2:5], v[156:159], v[40:43], v[2:5]
	s_waitcnt vmcnt(0) lgkmcnt(0)
	v_mfma_f32_16x16x32_bf16 v[6:9], v[160:163], v[44:47], v[6:9]
	v_mfma_f32_16x16x32_bf16 v[2:5], v[160:163], v[48:51], v[2:5]
	v_add_u32_e32 v23, 0x400, v23
	s_addk_i32 s17, 0x200
	s_cmpk_lt_u32 s17, 0x380
	s_cbranch_scc1 .LBB0_1150
; __device__ __forceinline__ float sigmoidf_(float x) { return __builtin_amdgcn_rcpf(1.f + __expf(-x)); }
; __device__ __forceinline__ u32x2 pack4(const f32x4& v) { u32x2 w; w.x = pk2(v[0], v[1]); w.y = pk2(v[2], v[3]); return w; }
; __device__ __forceinline__ f32x4 unpack4(const u32x2& x) { return (f32x4){bf2f(x.x & 0xffffu), __uint_as_float(x.x & 0xffff0000u), bf2f(x.y & 0xffffu), __uint_as_float(x.y & 0xffff0000u)}; }
; __device__ __forceinline__ void skinny_glu(Frame& F, int l) {
;     ...
;         const int col = n0 + 4 * (F.lane >> 4);
; #pragma unroll
;         for (int tt = 0; tt < 2; ++tt) { const int row = MPT + 16 * tt + (F.lane & 15);
;             const f32x4 zf = unpack4(*(const u32x2*)(Z + (size_t)row * 1024 + col)), sf = unpack4(*(const u32x2*)(P + (size_t)row * NPROJ + C_SZ + col));
;             f32x4 v = d[tt];
; #pragma unroll
;             for (int j = 0; j < 4; ++j) v[j] = zf[j] * sigmoidf_(v[j]) * sf[j];
;             *(u32x2*)(assm + (size_t)row * 1024 + col) = pack4(v); }
	s_lshl_b32 s17, s8, 7
	s_add_i32 s17, s17, s14
	v_or_b32_e32 v26, s17, v29
	v_ashrrev_i32_e32 v27, 31, v26
	v_lshlrev_b64 v[36:37], 1, v[26:27]
	v_lshl_add_u64 v[38:39], s[20:21], 0, v[36:37]
	v_lshl_add_u64 v[40:41], v[38:39], 0, v[98:99]
	global_load_dwordx2 v[40:41], v[40:41], off
	v_lshl_add_u64 v[42:43], v[16:17], 0, v[36:37]
	global_load_dwordx2 v[42:43], v[42:43], off
	v_mul_f32_e32 v6, 0xbfb8aa3b, v6
	v_mul_f32_e32 v7, 0xbfb8aa3b, v7
	v_mul_f32_e32 v8, 0xbfb8aa3b, v8
	v_mul_f32_e32 v9, 0xbfb8aa3b, v9
	v_exp_f32_e32 v6, v6
	v_exp_f32_e32 v7, v7
	v_exp_f32_e32 v8, v8
	v_exp_f32_e32 v9, v9
	v_add_f32_e32 v6, 1.0, v6
	v_add_f32_e32 v7, 1.0, v7
	v_add_f32_e32 v8, 1.0, v8
	v_add_f32_e32 v9, 1.0, v9
	v_rcp_f32_e32 v6, v6
	v_rcp_f32_e32 v7, v7
	v_rcp_f32_e32 v8, v8
	v_rcp_f32_e32 v9, v9
	v_lshl_add_u64 v[26:27], s[40:41], 0, v[36:37]
	v_mov_b32_e32 v25, v99
	v_mul_f32_e32 v2, 0xbfb8aa3b, v2
	v_mul_f32_e32 v3, 0xbfb8aa3b, v3
	v_mul_f32_e32 v4, 0xbfb8aa3b, v4
	v_mul_f32_e32 v5, 0xbfb8aa3b, v5
	v_exp_f32_e32 v2, v2
	v_exp_f32_e32 v3, v3
	v_exp_f32_e32 v4, v4
	v_exp_f32_e32 v5, v5
	v_add_f32_e32 v2, 1.0, v2
	v_add_f32_e32 v3, 1.0, v3
	v_add_f32_e32 v4, 1.0, v4
	v_add_f32_e32 v5, 1.0, v5
	v_rcp_f32_e32 v2, v2
	v_rcp_f32_e32 v3, v3
	v_rcp_f32_e32 v4, v4
	v_rcp_f32_e32 v5, v5
	s_mov_b64 s[22:23], -1
	s_waitcnt vmcnt(1)
	v_lshlrev_b32_e32 v44, 16, v40
	v_and_b32_e32 v45, 0xffff0000, v40
	v_lshlrev_b32_e32 v40, 16, v41
	v_and_b32_e32 v41, 0xffff0000, v41
	s_waitcnt vmcnt(0)
	v_lshlrev_b32_e32 v46, 16, v42
	v_and_b32_e32 v47, 0xffff0000, v42
	v_pk_mul_f32 v[6:7], v[6:7], v[44:45]
	v_lshlrev_b32_e32 v42, 16, v43
	v_and_b32_e32 v43, 0xffff0000, v43
	v_pk_mul_f32 v[8:9], v[8:9], v[40:41]
	v_pk_mul_f32 v[6:7], v[6:7], v[46:47]
	v_pk_mul_f32 v[8:9], v[8:9], v[42:43]
	v_cvt_pk_bf16_f32 v6, v6, v7
	v_cvt_pk_bf16_f32 v7, v8, v9
	v_lshl_add_u64 v[8:9], v[26:27], 0, v[98:99]
	global_store_dwordx2 v[8:9], v[6:7], off
	v_lshl_add_u64 v[6:7], v[38:39], 0, v[24:25]
	global_load_dwordx2 v[6:7], v[6:7], off
	v_lshl_add_u64 v[8:9], v[18:19], 0, v[36:37]
	global_load_dwordx2 v[8:9], v[8:9], off
	s_waitcnt vmcnt(1)
	v_lshlrev_b32_e32 v36, 16, v6
	v_and_b32_e32 v37, 0xffff0000, v6
	v_lshlrev_b32_e32 v6, 16, v7
	v_and_b32_e32 v7, 0xffff0000, v7
	s_waitcnt vmcnt(0)
	v_lshlrev_b32_e32 v38, 16, v8
	v_and_b32_e32 v39, 0xffff0000, v8
	v_pk_mul_f32 v[2:3], v[2:3], v[36:37]
	v_lshlrev_b32_e32 v8, 16, v9
	v_and_b32_e32 v9, 0xffff0000, v9
	v_pk_mul_f32 v[4:5], v[4:5], v[6:7]
	v_pk_mul_f32 v[2:3], v[2:3], v[38:39]
	v_pk_mul_f32 v[4:5], v[4:5], v[8:9]
	v_cvt_pk_bf16_f32 v2, v2, v3
	v_cvt_pk_bf16_f32 v3, v4, v5
	v_lshl_add_u64 v[4:5], v[26:27], 0, v[24:25]
	global_store_dwordx2 v[4:5], v[2:3], off
	s_branch .LBB0_1137
